# scan a-tile LDS reads batched; kv-up GEMM tile list rotated onto the workgroups idle in the q-up GEMM
# baseline (speedup 1.0000x reference)
.LBB0_523:
	s_add_i32 s3, s87, 64
	s_and_b32 s3, s3, 0xff
	v_mov_b32_e32 v4, v0
	s_cmpk_gt_i32 s3, 0x10f
	v_readfirstlane_b32 s27, v4
	s_cbranch_scc1 .LBB0_535
	v_lshlrev_b32_e32 v1, 4, v4
	v_add_u32_e32 v2, 0x2000, v1
	v_ashrrev_i32_e32 v5, 31, v2
	v_lshrrev_b32_e32 v5, 22, v5
	v_add_u32_e32 v5, v2, v5
	v_ashrrev_i32_e32 v5, 10, v5
	v_mul_i32_i24_e32 v6, 0x400, v5
	v_sub_u32_e32 v2, v2, v6
	v_lshrrev_b32_e32 v6, 4, v2
	v_bitop3_b32 v2, v6, v2, 32 bitop3:0x6c
	v_ashrrev_i32_e32 v6, 31, v2
	v_lshrrev_b32_e32 v6, 26, v6
	v_add_u32_e32 v6, v2, v6
	v_lshlrev_b32_e32 v8, 3, v5
	v_ashrrev_i32_e32 v7, 6, v6
	v_and_b32_e32 v8, -16, v8
	v_add_u32_e32 v8, v7, v8
	v_and_b32_e32 v7, 3, v7
	s_mov_b32 s0, 0x7fffe0
	v_lshrrev_b32_e32 v9, 2, v8
	v_lshlrev_b32_e32 v10, 1, v8
	v_and_or_b32 v7, v8, s0, v7
	v_and_b32_e32 v9, 4, v9
	v_and_b32_e32 v10, 24, v10
	v_and_b32_e32 v6, 0xc0, v6
	v_or3_b32 v7, v7, v9, v10
	v_sub_u32_e32 v2, v2, v6
	v_mov_b32_e32 v10, 1
	v_lshlrev_b32_e32 v5, 5, v5
	v_ashrrev_i16_sdwa v2, v10, sext(v2) dst_sel:DWORD dst_unused:UNUSED_PAD src0_sel:DWORD src1_sel:BYTE_0
	v_and_b32_e32 v5, 32, v5
	v_bfe_i32 v2, v2, 0, 16
	v_add_lshl_u32 v2, v5, v2, 1
	v_lshl_add_u32 v134, v7, 9, v2
	v_lshl_add_u32 v136, v8, 9, v2
	v_bfe_i32 v2, v4, 27, 1
	v_lshrrev_b32_e32 v2, 22, v2
	v_add_u32_e32 v2, v1, v2
	v_and_b32_e32 v2, 0xfffffc00, v2
	v_sub_u32_e32 v1, v1, v2
	v_ashrrev_i32_e32 v5, 31, v4
	v_lshrrev_b32_e32 v2, 4, v1
	v_lshrrev_b32_e32 v5, 26, v5
	v_bitop3_b32 v2, v2, v1, 32 bitop3:0x6c
	v_ashrrev_i32_e32 v1, 31, v1
	v_add_u32_e32 v5, v4, v5
	s_ashr_i32 s1, s27, 6
	v_lshrrev_b32_e32 v1, 26, v1
	v_ashrrev_i32_e32 v5, 6, v5
	s_ashr_i32 s4, s27, 8
	s_lshl_b32 s74, s1, 10
	v_add_u32_e32 v1, v2, v1
	v_lshlrev_b32_e32 v6, 3, v5
	s_add_u32 s75, s28, 0x1b20000
	v_ashrrev_i32_e32 v1, 6, v1
	v_and_b32_e32 v6, -16, v6
	s_mov_b64 s[14:15], s[76:77]
	s_addc_u32 s76, s29, 0
	v_add_u32_e32 v6, v1, v6
	v_and_b32_e32 v7, 3, v1
	s_ashr_i32 s77, s3, 31
	v_and_or_b32 v7, v6, s0, v7
	s_lshr_b32 s0, s77, 29
	s_add_i32 s0, s3, s0
	s_ashr_i32 s5, s0, 3
	s_and_b32 s0, s0, -8
	s_sub_i32 s0, s3, s0
	s_cmp_lt_i32 s0, 0
	s_cselect_b32 s6, 35, 34
	s_mul_i32 s0, s0, s6
	s_add_i32 s0, s0, s5
	s_ashr_i32 s5, s0, 31
	s_lshr_b32 s5, s5, 27
	v_mul_i32_i24_e32 v1, 64, v1
	s_add_i32 s5, s0, s5
	v_sub_u32_e32 v1, v2, v1
	s_ashr_i32 s6, s5, 5
	v_lshrrev_b32_e32 v8, 2, v6
	v_lshlrev_b32_e32 v9, 1, v6
	v_lshlrev_b32_e32 v5, 5, v5
	v_ashrrev_i16_sdwa v1, v10, sext(v1) dst_sel:DWORD dst_unused:UNUSED_PAD src0_sel:DWORD src1_sel:BYTE_0
	s_lshl_b32 s10, s6, 2
	v_and_b32_e32 v8, 4, v8
	v_and_b32_e32 v9, 24, v9
	v_and_b32_e32 v5, 32, v5
	v_bfe_i32 v1, v1, 0, 16
	s_sub_i32 s6, 34, s10
	v_or3_b32 v7, v7, v8, v9
	v_add_lshl_u32 v1, v5, v1, 1
	s_min_u32 s11, s6, 4
	s_andn2_b32 s5, s5, 31
	v_lshl_add_u32 v2, v7, 9, v1
	s_sub_i32 s5, s0, s5
	v_cvt_f32_ubyte0_e32 v7, s11
	v_cvt_f32_i32_e32 v5, s5
	v_rcp_iflag_f32_e32 v8, v7
	v_lshl_add_u32 v138, v6, 9, v1
	s_ashr_i32 s0, s5, 30
	s_or_b32 s0, s0, 1
	v_mul_f32_e32 v1, v5, v8
	v_trunc_f32_e32 v1, v1
	v_fma_f32 v5, -v1, v7, v5
	v_cvt_i32_f32_e32 v1, v1
	v_cmp_ge_f32_e64 s[6:7], |v5|, v7
	s_and_b64 s[6:7], s[6:7], exec
	s_cselect_b32 s0, s0, 0
	v_readfirstlane_b32 s6, v1
	s_add_i32 s0, s6, s0
	s_mul_i32 s6, s0, s11
	s_sub_i32 s5, s5, s6
	s_sext_i32_i8 s5, s5
	s_add_i32 s16, s10, s5
	s_ashr_i32 s17, s16, 31
	s_bfe_i64 s[10:11], s[0:1], 0x80000
	s_lshl_b64 s[6:7], s[16:17], 17
	s_lshl_b64 s[10:11], s[10:11], 17
	s_add_u32 s18, s75, s10
	s_addc_u32 s19, s76, s11
	s_add_i32 s17, s74, 0
	s_add_i32 m0, s17, 0x10000
	v_writelane_b32 v254, s54, 32
	global_load_lds_dwordx4 v2, s[18:19]
	s_add_i32 m0, s17, 0x12000
	s_add_u32 s42, s14, s6
	global_load_lds_dwordx4 v134, s[18:19]
	s_addc_u32 s43, s15, s7
	s_mov_b32 m0, s17
	s_add_i32 s78, s17, 0x2000
	global_load_lds_dwordx4 v138, s[42:43]
	s_mov_b32 m0, s78
	s_add_u32 s6, s18, 0x10000
	global_load_lds_dwordx4 v136, s[42:43]
	s_addc_u32 s7, s19, 0
	s_add_i32 m0, s17, 0x14000
	v_writelane_b32 v254, s55, 33
	global_load_lds_dwordx4 v2, s[6:7]
	s_add_i32 m0, s17, 0x16000
	v_writelane_b32 v254, s52, 30
	global_load_lds_dwordx4 v134, s[6:7]
	s_add_u32 s6, s42, 0x10000
	s_addc_u32 s7, s43, 0
	s_add_i32 s79, s17, 0x4000
	s_mov_b32 m0, s79
	s_add_i32 s80, s17, 0x6000
	global_load_lds_dwordx4 v138, s[6:7]
	s_mov_b32 m0, s80
	v_writelane_b32 v254, s53, 31
	global_load_lds_dwordx4 v136, s[6:7]
	v_writelane_b32 v254, s87, 29
	v_mov_b32_e32 v219, 1
	s_cmp_lg_u32 s4, 1
	s_cbranch_scc1 .LBB0_526
	s_barrier

.LBB0_573:
	s_add_i32 s46, s44, 1
	v_min_i32_e32 v20, s46, v181
	v_sub_u32_e32 v21, v181, v20
	v_cndmask_b32_e64 v20, v21, v20, s[18:19]
	v_lshl_add_u32 v20, v20, 6, v183
	v_ashrrev_i32_e32 v21, 31, v20
	v_lshl_add_u64 v[22:23], v[20:21], 1, v[206:207]
	global_load_dwordx4 v[54:57], v[22:23], off
	v_ashrrev_i32_e32 v22, 6, v20
	v_ashrrev_i32_e32 v23, 31, v22
	v_lshlrev_b64 v[24:25], 9, v[22:23]
	v_lshl_add_u64 v[24:25], v[208:209], 0, v[24:25]
	v_lshlrev_b64 v[20:21], 8, v[20:21]
	global_load_dword v187, v[24:25], off
	v_lshl_add_u64 v[24:25], v[210:211], 0, v[20:21]
	s_movk_i32 s45, 0x2000
	v_add_co_u32_e32 v26, vcc, s45, v24
	s_movk_i32 s47, 0x3000
	s_nop 0
	v_addc_co_u32_e32 v27, vcc, 0, v25, vcc
	global_load_dwordx4 v[58:61], v[24:25], off
	v_add_co_u32_e32 v24, vcc, s47, v24
	v_lshl_add_u64 v[20:21], v[212:213], 0, v[20:21]
	s_nop 0
	v_addc_co_u32_e32 v25, vcc, 0, v25, vcc
	global_load_dwordx4 v[70:73], v[26:27], off offset:-4096
	global_load_dwordx4 v[74:77], v[26:27], off
	global_load_dwordx4 v[82:85], v[24:25], off
	global_load_dwordx4 v[90:93], v[20:21], off
	v_add_co_u32_e32 v24, vcc, s45, v20
	v_add_u32_e32 v158, v163, v150
	s_nop 0
	v_addc_co_u32_e32 v25, vcc, 0, v21, vcc
	v_add_co_u32_e32 v20, vcc, s47, v20
	global_load_dwordx4 v[94:97], v[24:25], off offset:-4096
	global_load_dwordx4 v[98:101], v[24:25], off
	v_addc_co_u32_e32 v21, vcc, 0, v21, vcc
	global_load_dwordx4 v[102:105], v[20:21], off
	v_lshl_add_u64 v[20:21], v[2:3], 0, v[22:23]
	v_lshlrev_b64 v[20:21], 14, v[20:21]
	v_lshl_or_b32 v20, v198, 7, v20
	v_lshl_add_u64 v[20:21], v[152:153], 0, v[20:21]
	global_load_dwordx4 v[86:89], v[20:21], off
	global_load_dwordx4 v[78:81], v[20:21], off offset:32
	global_load_dwordx4 v[66:69], v[20:21], off offset:64
	global_load_dwordx4 v[62:65], v[20:21], off offset:96
	s_waitcnt lgkmcnt(0)
	s_barrier
	ds_read_b128 v[106:109], v173 offset:28160
	ds_read_b128 v[234:237], v158 offset:45568
	ds_read_b128 v[110:113], v173 offset:28192
	ds_read_b128 v[238:241], v158 offset:45600
	ds_read_b128 v[134:137], v173 offset:28224
	ds_read_b128 v[242:245], v158 offset:45632
	ds_read_b128 v[114:117], v173 offset:28256
	ds_read_b128 v[246:249], v158 offset:45664
	ds_read_b128 v[118:121], v173 offset:28288
	ds_read_b128 v[250:253], v158 offset:45696
	ds_read_b128 v[122:125], v173 offset:28320
	ds_read_b128 v[126:129], v173 offset:28352
	ds_read_b128 v[130:133], v173 offset:28384
	s_and_b32 s45, s44, 1
	s_mul_i32 s47, s45, 0x1200
	v_add_u32_e32 v189, s47, v154
	v_add3_u32 v189, v189, v165, v150
	s_waitcnt lgkmcnt(11)
	v_mfma_f32_32x32x16_bf16 v[20:35], v[106:109], v[234:237], 0
	ds_read_b128 v[234:237], v158 offset:45728
	s_waitcnt lgkmcnt(10)
	v_mfma_f32_32x32x16_bf16 v[20:35], v[110:113], v[238:241], v[20:35]
	ds_read_b128 v[238:241], v158 offset:45760
	s_waitcnt lgkmcnt(9)
	v_mfma_f32_32x32x16_bf16 v[20:35], v[134:137], v[242:245], v[20:35]
	ds_read_b128 v[242:245], v158 offset:45792
	s_waitcnt lgkmcnt(8)
	v_mfma_f32_32x32x16_bf16 v[20:35], v[114:117], v[246:249], v[20:35]
	s_waitcnt lgkmcnt(6)
	v_mfma_f32_32x32x16_bf16 v[20:35], v[118:121], v[250:253], v[20:35]
	s_waitcnt lgkmcnt(2)
	v_mfma_f32_32x32x16_bf16 v[20:35], v[122:125], v[234:237], v[20:35]
	s_waitcnt lgkmcnt(1)
	v_mfma_f32_32x32x16_bf16 v[20:35], v[126:129], v[238:241], v[20:35]
	s_waitcnt lgkmcnt(0)
	v_mfma_f32_32x32x16_bf16 v[20:35], v[130:133], v[242:245], v[20:35]
	s_nop 11
	v_cndmask_b32_e64 v20, 0, v20, s[78:79]
	v_cndmask_b32_e64 v21, 0, v21, s[80:81]
	v_bfe_u32 v158, v20, 16, 1
	v_cndmask_b32_e64 v22, 0, v22, s[82:83]
	v_bfe_u32 v159, v21, 16, 1
	v_add3_u32 v20, v20, v158, s73
	v_add3_u32 v21, v21, v159, s73
	ds_write_b16_d16_hi v175, v20 offset:8704
	ds_write_b16_d16_hi v175, v21 offset:8848
	v_bfe_u32 v20, v22, 16, 1
	v_add3_u32 v20, v22, v20, s73
	ds_write_b16_d16_hi v175, v20 offset:8992
	v_cndmask_b32_e64 v20, 0, v23, s[84:85]
	v_bfe_u32 v21, v20, 16, 1
	v_add3_u32 v20, v20, v21, s73
	ds_write_b16_d16_hi v175, v20 offset:9136
	v_cndmask_b32_e64 v20, 0, v24, s[86:87]
	v_bfe_u32 v21, v20, 16, 1
	v_add3_u32 v20, v20, v21, s73
	ds_write_b16_d16_hi v175, v20 offset:9856
	v_cndmask_b32_e64 v20, 0, v25, s[88:89]
	v_bfe_u32 v21, v20, 16, 1
	v_add3_u32 v20, v20, v21, s73
	ds_write_b16_d16_hi v175, v20 offset:10000
	v_cndmask_b32_e64 v20, 0, v26, s[90:91]
	v_bfe_u32 v21, v20, 16, 1
	v_add3_u32 v20, v20, v21, s73
	ds_write_b16_d16_hi v175, v20 offset:10144
	v_cndmask_b32_e64 v20, 0, v27, s[92:93]
	v_bfe_u32 v21, v20, 16, 1
	v_add3_u32 v20, v20, v21, s73
	ds_write_b16_d16_hi v175, v20 offset:10288
	v_cndmask_b32_e64 v20, 0, v28, s[94:95]
	v_bfe_u32 v21, v20, 16, 1
	v_add3_u32 v20, v20, v21, s73
	ds_write_b16_d16_hi v175, v20 offset:11008
	v_cndmask_b32_e64 v20, 0, v29, s[96:97]
	v_bfe_u32 v21, v20, 16, 1
	v_add3_u32 v20, v20, v21, s73
	ds_write_b16_d16_hi v175, v20 offset:11152
	v_cndmask_b32_e64 v20, 0, v30, s[16:17]
	v_bfe_u32 v21, v20, 16, 1
	v_add3_u32 v20, v20, v21, s73
	ds_write_b16_d16_hi v175, v20 offset:11296
	v_cndmask_b32_e64 v20, 0, v31, s[8:9]
	v_bfe_u32 v21, v20, 16, 1
	v_add3_u32 v20, v20, v21, s73
	ds_write_b16_d16_hi v175, v20 offset:11440
	v_cndmask_b32_e64 v20, 0, v32, s[0:1]
	v_bfe_u32 v21, v20, 16, 1
	v_add3_u32 v20, v20, v21, s73
	ds_write_b16_d16_hi v175, v20 offset:12160
	v_cndmask_b32_e64 v20, 0, v33, s[10:11]
	v_bfe_u32 v21, v20, 16, 1
	v_add3_u32 v20, v20, v21, s73
	ds_write_b16_d16_hi v175, v20 offset:12304
	v_cndmask_b32_e64 v20, 0, v34, s[12:13]
	v_bfe_u32 v21, v20, 16, 1
	v_add3_u32 v20, v20, v21, s73
	ds_write_b16_d16_hi v175, v20 offset:12448
	v_cndmask_b32_e64 v20, 0, v35, s[14:15]
	v_bfe_u32 v21, v20, 16, 1
	v_add3_u32 v20, v20, v21, s73
	ds_write_b16_d16_hi v175, v20 offset:12592
	s_waitcnt lgkmcnt(0)
	s_barrier
	s_and_saveexec_b64 vcc, s[6:7]
	s_cbranch_execz .LBB0_575
	v_mov_b32_e32 v20, s44
	v_cndmask_b32_e64 v20, v185, v20, s[18:19]
	v_lshl_add_u32 v230, v20, 6, v183
	ds_read_b128 v[20:23], v169
	ds_read_b128 v[158:161], v169 offset:32
	v_ashrrev_i32_e32 v231, 31, v230
	s_waitcnt lgkmcnt(1)
	v_mfma_f32_32x32x16_bf16 v[20:35], v[106:109], v[20:23], 0
	ds_read_b128 v[106:109], v169 offset:64
	s_waitcnt lgkmcnt(1)
	v_mfma_f32_32x32x16_bf16 v[20:35], v[110:113], v[158:161], v[20:35]
	s_waitcnt lgkmcnt(0)
	v_mfma_f32_32x32x16_bf16 v[20:35], v[134:137], v[106:109], v[20:35]
	ds_read_b128 v[106:109], v169 offset:96
	s_waitcnt lgkmcnt(0)
	v_mfma_f32_32x32x16_bf16 v[20:35], v[114:117], v[106:109], v[20:35]
	ds_read_b128 v[106:109], v169 offset:128
	s_waitcnt lgkmcnt(0)
	v_mfma_f32_32x32x16_bf16 v[20:35], v[118:121], v[106:109], v[20:35]
	ds_read_b128 v[106:109], v169 offset:160
	s_waitcnt lgkmcnt(0)
	v_mfma_f32_32x32x16_bf16 v[20:35], v[122:125], v[106:109], v[20:35]
	ds_read_b128 v[106:109], v169 offset:192
	s_waitcnt lgkmcnt(0)
	v_mfma_f32_32x32x16_bf16 v[20:35], v[126:129], v[106:109], v[20:35]
	ds_read_b128 v[106:109], v169 offset:224
	s_waitcnt lgkmcnt(0)
	v_mfma_f32_32x32x16_bf16 v[20:35], v[130:133], v[106:109], v[20:35]
	ds_read_b128 v[106:109], v177 offset:8704
	ds_read_b128 v[110:113], v177 offset:8736
	ds_read_b128 v[114:117], v189 offset:17920
	ds_read_b128 v[118:121], v189 offset:17952
	s_waitcnt lgkmcnt(1)
	v_mfma_f32_32x32x16_bf16 v[20:35], v[106:109], v[114:117], v[20:35]
	s_waitcnt lgkmcnt(0)
	v_mfma_f32_32x32x16_bf16 v[20:35], v[110:113], v[118:121], v[20:35]
	ds_read_b128 v[106:109], v177 offset:8768
	ds_read_b128 v[110:113], v189 offset:17984
	s_waitcnt lgkmcnt(0)
	v_mfma_f32_32x32x16_bf16 v[20:35], v[106:109], v[110:113], v[20:35]
	ds_read_b128 v[106:109], v177 offset:8800
	ds_read_b128 v[110:113], v189 offset:18016
	s_waitcnt lgkmcnt(0)
	v_mfma_f32_32x32x16_bf16 v[20:35], v[106:109], v[110:113], v[20:35]
	v_lshl_add_u64 v[106:107], v[214:215], 0, v[230:231]
	v_mov_b32_e32 v109, v107
	s_nop 9
	v_bfe_u32 v108, v20, 16, 1
	v_add3_u32 v20, v20, v108, s73
	v_or_b32_e32 v108, v106, v162
	v_lshlrev_b64 v[108:109], 11, v[108:109]
	v_lshl_add_u64 v[108:109], v[216:217], 0, v[108:109]
	global_store_short_d16_hi v[108:109], v20, off
	v_bfe_u32 v20, v21, 16, 1
	v_add3_u32 v108, v21, v20, s73
	v_or_b32_e32 v20, v106, v168
	v_mov_b32_e32 v21, v107
	v_lshlrev_b64 v[20:21], 11, v[20:21]
	v_lshl_add_u64 v[20:21], v[216:217], 0, v[20:21]
	global_store_short_d16_hi v[20:21], v108, off
	v_bfe_u32 v20, v22, 16, 1
	v_add3_u32 v22, v22, v20, s73
	v_or_b32_e32 v20, v106, v170
	v_mov_b32_e32 v21, v107
	v_lshlrev_b64 v[20:21], 11, v[20:21]
	v_lshl_add_u64 v[20:21], v[216:217], 0, v[20:21]
	global_store_short_d16_hi v[20:21], v22, off
	v_bfe_u32 v20, v23, 16, 1
	v_add3_u32 v22, v23, v20, s73
	v_or_b32_e32 v20, v106, v172
	v_mov_b32_e32 v21, v107
	v_lshlrev_b64 v[20:21], 11, v[20:21]
	v_lshl_add_u64 v[20:21], v[216:217], 0, v[20:21]
	global_store_short_d16_hi v[20:21], v22, off
	v_bfe_u32 v20, v24, 16, 1
	v_add3_u32 v22, v24, v20, s73
	v_or_b32_e32 v20, v106, v174
	v_mov_b32_e32 v21, v107
	v_lshlrev_b64 v[20:21], 11, v[20:21]
	v_lshl_add_u64 v[20:21], v[216:217], 0, v[20:21]
	global_store_short_d16_hi v[20:21], v22, off
	v_bfe_u32 v20, v25, 16, 1
	v_add3_u32 v22, v25, v20, s73
	v_or_b32_e32 v20, v106, v176
	v_mov_b32_e32 v21, v107
	v_lshlrev_b64 v[20:21], 11, v[20:21]
	v_lshl_add_u64 v[20:21], v[216:217], 0, v[20:21]
	global_store_short_d16_hi v[20:21], v22, off
	v_bfe_u32 v20, v26, 16, 1
	v_add3_u32 v22, v26, v20, s73
	v_or_b32_e32 v20, v106, v178
	v_mov_b32_e32 v21, v107
	v_lshlrev_b64 v[20:21], 11, v[20:21]
	v_lshl_add_u64 v[20:21], v[216:217], 0, v[20:21]
	global_store_short_d16_hi v[20:21], v22, off
	v_bfe_u32 v20, v27, 16, 1
	v_add3_u32 v22, v27, v20, s73
	v_or_b32_e32 v20, v106, v180
	v_mov_b32_e32 v21, v107
	v_lshlrev_b64 v[20:21], 11, v[20:21]
	v_lshl_add_u64 v[20:21], v[216:217], 0, v[20:21]
	global_store_short_d16_hi v[20:21], v22, off
	v_bfe_u32 v20, v28, 16, 1
	v_add3_u32 v22, v28, v20, s73
	v_or_b32_e32 v20, v106, v182
	v_mov_b32_e32 v21, v107
	v_lshlrev_b64 v[20:21], 11, v[20:21]
	v_lshl_add_u64 v[20:21], v[216:217], 0, v[20:21]
	global_store_short_d16_hi v[20:21], v22, off
	v_bfe_u32 v20, v29, 16, 1
	v_add3_u32 v22, v29, v20, s73
	v_or_b32_e32 v20, v106, v184
	v_mov_b32_e32 v21, v107
	v_lshlrev_b64 v[20:21], 11, v[20:21]
	v_lshl_add_u64 v[20:21], v[216:217], 0, v[20:21]
	global_store_short_d16_hi v[20:21], v22, off
	v_bfe_u32 v20, v30, 16, 1
	v_add3_u32 v22, v30, v20, s73
	v_or_b32_e32 v20, v106, v186
	v_mov_b32_e32 v21, v107
	v_lshlrev_b64 v[20:21], 11, v[20:21]
	v_lshl_add_u64 v[20:21], v[216:217], 0, v[20:21]
	global_store_short_d16_hi v[20:21], v22, off
	v_bfe_u32 v20, v31, 16, 1
	v_add3_u32 v22, v31, v20, s73
	v_or_b32_e32 v20, v106, v188
	v_mov_b32_e32 v21, v107
	v_lshlrev_b64 v[20:21], 11, v[20:21]
	v_lshl_add_u64 v[20:21], v[216:217], 0, v[20:21]
	global_store_short_d16_hi v[20:21], v22, off
	v_bfe_u32 v20, v32, 16, 1
	v_add3_u32 v22, v32, v20, s73
	v_or_b32_e32 v20, v106, v190
	v_mov_b32_e32 v21, v107
	v_lshlrev_b64 v[20:21], 11, v[20:21]
	v_lshl_add_u64 v[20:21], v[216:217], 0, v[20:21]
	global_store_short_d16_hi v[20:21], v22, off
	v_bfe_u32 v20, v33, 16, 1
	v_add3_u32 v22, v33, v20, s73
	v_or_b32_e32 v20, v106, v192
	v_mov_b32_e32 v21, v107
	v_lshlrev_b64 v[20:21], 11, v[20:21]
	v_lshl_add_u64 v[20:21], v[216:217], 0, v[20:21]
	global_store_short_d16_hi v[20:21], v22, off
	v_bfe_u32 v20, v34, 16, 1
	v_add3_u32 v22, v34, v20, s73
	v_or_b32_e32 v20, v106, v194
	v_mov_b32_e32 v21, v107
	v_lshlrev_b64 v[20:21], 11, v[20:21]
	v_lshl_add_u64 v[20:21], v[216:217], 0, v[20:21]
	global_store_short_d16_hi v[20:21], v22, off
	v_bfe_u32 v20, v35, 16, 1
	v_or_b32_e32 v106, v106, v196
	v_add3_u32 v22, v35, v20, s73
	v_lshlrev_b64 v[20:21], 11, v[106:107]
	v_lshl_add_u64 v[20:21], v[216:217], 0, v[20:21]
	global_store_short_d16_hi v[20:21], v22, off
